# back-edge rotation in the four GEMM K-loops: counter and pointer bumps plus the exit compare moved in front of the loop-closing barrier, only the branch stays behind it
# baseline (speedup 1.0000x reference)
.LBB0_88:
	ds_read_b128 v[146:149], v162
	ds_read_b128 v[150:153], v162 offset:1024
	ds_read_b128 v[154:157], v162 offset:2048
	ds_read_b128 v[166:169], v162 offset:3072
	ds_read_b128 v[170:173], v163
	ds_read_b128 v[174:177], v163 offset:1024
	ds_read_b128 v[178:181], v163 offset:2048
	ds_read_b128 v[182:185], v163 offset:3072
	s_add_u32 s8, s6, 0xfffc0080
	s_addc_u32 s9, s7, -1
	s_cmp_eq_u32 s54, 12
	s_cselect_b32 s35, s5, s9
	s_cselect_b32 s34, s10, s8
	s_cselect_b32 s9, s11, s53
	s_cselect_b32 s8, s26, s27
	v_lshl_add_u64 v[158:159], s[6:7], 0, v[138:139]
	s_add_i32 m0, s19, 0xc000
	ds_read_b128 v[190:193], v164
	ds_read_b128 v[194:197], v164 offset:1024
	ds_read_b128 v[198:201], v164 offset:2048
	ds_read_b128 v[202:205], v164 offset:3072
	ds_read_b128 v[206:209], v164 offset:4096
	ds_read_b128 v[210:213], v164 offset:5120
	ds_read_b128 v[214:217], v164 offset:6144
	ds_read_b128 v[218:221], v164 offset:7168
	global_load_lds_dwordx4 v[158:159], off
	v_lshl_add_u64 v[158:159], s[6:7], 0, v[140:141]
	s_add_i32 m0, s19, 0xe000
	s_nop 0
	global_load_lds_dwordx4 v[158:159], off
	s_waitcnt vmcnt(8)
	s_waitcnt lgkmcnt(0)
	s_barrier
	s_setprio 1
	s_waitcnt lgkmcnt(0)
	v_mfma_f32_16x16x32_bf16 v[124:127], v[146:149], v[190:193], v[124:127]
	v_mfma_f32_16x16x32_bf16 v[120:123], v[154:157], v[190:193], v[120:123]
	v_mfma_f32_16x16x32_bf16 v[108:111], v[146:149], v[198:201], v[108:111]
	v_mfma_f32_16x16x32_bf16 v[104:107], v[154:157], v[198:201], v[104:107]
	v_mfma_f32_16x16x32_bf16 v[92:95], v[146:149], v[206:209], v[92:95]
	v_mfma_f32_16x16x32_bf16 v[88:91], v[154:157], v[206:209], v[88:91]
	v_mfma_f32_16x16x32_bf16 v[76:79], v[146:149], v[214:217], v[76:79]
	v_mfma_f32_16x16x32_bf16 v[72:75], v[154:157], v[214:217], v[72:75]
	v_mfma_f32_16x16x32_bf16 v[124:127], v[150:153], v[194:197], v[124:127]
	v_mfma_f32_16x16x32_bf16 v[120:123], v[166:169], v[194:197], v[120:123]
	v_mfma_f32_16x16x32_bf16 v[108:111], v[150:153], v[202:205], v[108:111]
	v_mfma_f32_16x16x32_bf16 v[104:107], v[166:169], v[202:205], v[104:107]
	v_mfma_f32_16x16x32_bf16 v[92:95], v[150:153], v[210:213], v[92:95]
	v_mfma_f32_16x16x32_bf16 v[88:91], v[166:169], v[210:213], v[88:91]
	v_mfma_f32_16x16x32_bf16 v[76:79], v[150:153], v[218:221], v[76:79]
	v_mfma_f32_16x16x32_bf16 v[72:75], v[166:169], v[218:221], v[72:75]
	s_setprio 0
	s_setprio 1
	v_mfma_f32_16x16x32_bf16 v[116:119], v[170:173], v[190:193], v[116:119]
	v_mfma_f32_16x16x32_bf16 v[112:115], v[178:181], v[190:193], v[112:115]
	v_mfma_f32_16x16x32_bf16 v[100:103], v[170:173], v[198:201], v[100:103]
	v_mfma_f32_16x16x32_bf16 v[96:99], v[178:181], v[198:201], v[96:99]
	v_mfma_f32_16x16x32_bf16 v[84:87], v[170:173], v[206:209], v[84:87]
	v_mfma_f32_16x16x32_bf16 v[80:83], v[178:181], v[206:209], v[80:83]
	v_mfma_f32_16x16x32_bf16 v[68:71], v[170:173], v[214:217], v[68:71]
	v_mfma_f32_16x16x32_bf16 v[64:67], v[178:181], v[214:217], v[64:67]
	v_mfma_f32_16x16x32_bf16 v[116:119], v[174:177], v[194:197], v[116:119]
	v_mfma_f32_16x16x32_bf16 v[112:115], v[182:185], v[194:197], v[112:115]
	v_mfma_f32_16x16x32_bf16 v[100:103], v[174:177], v[202:205], v[100:103]
	v_mfma_f32_16x16x32_bf16 v[96:99], v[182:185], v[202:205], v[96:99]
	v_mfma_f32_16x16x32_bf16 v[84:87], v[174:177], v[210:213], v[84:87]
	v_mfma_f32_16x16x32_bf16 v[80:83], v[182:185], v[210:213], v[80:83]
	v_mfma_f32_16x16x32_bf16 v[68:71], v[174:177], v[218:221], v[68:71]
	v_mfma_f32_16x16x32_bf16 v[64:67], v[182:185], v[218:221], v[64:67]
	s_setprio 0
	s_barrier
	s_add_i32 s55, s45, s33
	v_lshl_add_u64 v[158:159], s[8:9], 0, v[130:131]
	s_mov_b32 m0, s55
	ds_read_b128 v[190:193], v164 offset:16384
	ds_read_b128 v[194:197], v164 offset:17408
	ds_read_b128 v[198:201], v164 offset:18432
	ds_read_b128 v[202:205], v164 offset:19456
	ds_read_b128 v[206:209], v164 offset:20480
	ds_read_b128 v[210:213], v164 offset:21504
	ds_read_b128 v[214:217], v164 offset:22528
	ds_read_b128 v[218:221], v164 offset:23552
	global_load_lds_dwordx4 v[158:159], off
	s_add_i32 m0, s55, 0x2000
	s_add_u32 s56, s8, 0x40000
	v_lshl_add_u64 v[186:187], s[8:9], 0, v[134:135]
	s_addc_u32 s57, s9, 0
	s_add_i32 s55, s46, s33
	global_load_lds_dwordx4 v[186:187], off
	v_lshl_add_u64 v[222:223], s[56:57], 0, v[130:131]
	s_mov_b32 m0, s55
	v_lshl_add_u64 v[224:225], s[34:35], 0, v[132:133]
	global_load_lds_dwordx4 v[222:223], off
	v_lshl_add_u64 v[222:223], s[56:57], 0, v[134:135]
	s_add_i32 m0, s55, 0x2000
	s_nop 0
	global_load_lds_dwordx4 v[222:223], off
	v_lshl_add_u64 v[222:223], s[34:35], 0, v[128:129]
	s_mov_b32 m0, s19
	s_nop 0
	global_load_lds_dwordx4 v[222:223], off
	s_mov_b32 m0, s36
	s_nop 0
	global_load_lds_dwordx4 v[224:225], off
	s_waitcnt vmcnt(8)
	s_waitcnt lgkmcnt(0)
	s_barrier
	s_setprio 1
	s_waitcnt lgkmcnt(0)
	v_mfma_f32_16x16x32_bf16 v[60:63], v[146:149], v[190:193], v[60:63]
	v_mfma_f32_16x16x32_bf16 v[56:59], v[154:157], v[190:193], v[56:59]
	v_mfma_f32_16x16x32_bf16 v[44:47], v[146:149], v[198:201], v[44:47]
	v_mfma_f32_16x16x32_bf16 v[40:43], v[154:157], v[198:201], v[40:43]
	v_mfma_f32_16x16x32_bf16 v[28:31], v[146:149], v[206:209], v[28:31]
	v_mfma_f32_16x16x32_bf16 v[24:27], v[154:157], v[206:209], v[24:27]
	v_mfma_f32_16x16x32_bf16 v[12:15], v[146:149], v[214:217], v[12:15]
	v_mfma_f32_16x16x32_bf16 v[8:11], v[154:157], v[214:217], v[8:11]
	v_mfma_f32_16x16x32_bf16 v[60:63], v[150:153], v[194:197], v[60:63]
	v_mfma_f32_16x16x32_bf16 v[56:59], v[166:169], v[194:197], v[56:59]
	v_mfma_f32_16x16x32_bf16 v[44:47], v[150:153], v[202:205], v[44:47]
	v_mfma_f32_16x16x32_bf16 v[40:43], v[166:169], v[202:205], v[40:43]
	v_mfma_f32_16x16x32_bf16 v[28:31], v[150:153], v[210:213], v[28:31]
	v_mfma_f32_16x16x32_bf16 v[24:27], v[166:169], v[210:213], v[24:27]
	v_mfma_f32_16x16x32_bf16 v[12:15], v[150:153], v[218:221], v[12:15]
	v_mfma_f32_16x16x32_bf16 v[8:11], v[166:169], v[218:221], v[8:11]
	s_setprio 0
	s_setprio 1
	v_mfma_f32_16x16x32_bf16 v[52:55], v[170:173], v[190:193], v[52:55]
	v_mfma_f32_16x16x32_bf16 v[48:51], v[178:181], v[190:193], v[48:51]
	v_mfma_f32_16x16x32_bf16 v[36:39], v[170:173], v[198:201], v[36:39]
	v_mfma_f32_16x16x32_bf16 v[32:35], v[178:181], v[198:201], v[32:35]
	v_mfma_f32_16x16x32_bf16 v[20:23], v[170:173], v[206:209], v[20:23]
	v_mfma_f32_16x16x32_bf16 v[16:19], v[178:181], v[206:209], v[16:19]
	v_mfma_f32_16x16x32_bf16 v[4:7], v[170:173], v[214:217], v[4:7]
	v_mfma_f32_16x16x32_bf16 v[0:3], v[178:181], v[214:217], v[0:3]
	v_mfma_f32_16x16x32_bf16 v[52:55], v[174:177], v[194:197], v[52:55]
	v_mfma_f32_16x16x32_bf16 v[48:51], v[182:185], v[194:197], v[48:51]
	v_mfma_f32_16x16x32_bf16 v[36:39], v[174:177], v[202:205], v[36:39]
	v_mfma_f32_16x16x32_bf16 v[32:35], v[182:185], v[202:205], v[32:35]
	v_mfma_f32_16x16x32_bf16 v[20:23], v[174:177], v[210:213], v[20:23]
	v_mfma_f32_16x16x32_bf16 v[16:19], v[182:185], v[210:213], v[16:19]
	v_mfma_f32_16x16x32_bf16 v[4:7], v[174:177], v[218:221], v[4:7]
	v_mfma_f32_16x16x32_bf16 v[0:3], v[182:185], v[218:221], v[0:3]
	s_setprio 0
	s_barrier
	s_add_i32 s55, 0, 0x18000
	v_add_u32_e32 v165, s55, v160
	s_add_i32 s56, 0, 0x1c000
	ds_read_b128 v[146:149], v165
	ds_read_b128 v[150:153], v165 offset:1024
	ds_read_b128 v[154:157], v165 offset:2048
	ds_read_b128 v[166:169], v165 offset:3072
	v_add_u32_e32 v165, s56, v160
	ds_read_b128 v[170:173], v165
	ds_read_b128 v[174:177], v165 offset:1024
	ds_read_b128 v[178:181], v165 offset:2048
	ds_read_b128 v[182:185], v165 offset:3072
	s_add_u32 s34, s34, 0x40000
	s_addc_u32 s35, s35, 0
	s_mov_b32 m0, s37
	v_lshl_add_u64 v[226:227], s[34:35], 0, v[128:129]
	ds_read_b128 v[190:193], v164 offset:32768
	ds_read_b128 v[194:197], v164 offset:33792
	ds_read_b128 v[198:201], v164 offset:34816
	ds_read_b128 v[202:205], v164 offset:35840
	ds_read_b128 v[206:209], v164 offset:36864
	ds_read_b128 v[210:213], v164 offset:37888
	ds_read_b128 v[214:217], v164 offset:38912
	ds_read_b128 v[218:221], v164 offset:39936
	global_load_lds_dwordx4 v[226:227], off
	v_lshl_add_u64 v[226:227], s[34:35], 0, v[132:133]
	s_mov_b32 m0, s38
	s_nop 0
	global_load_lds_dwordx4 v[226:227], off
	s_waitcnt vmcnt(8)
	s_waitcnt lgkmcnt(0)
	s_barrier
	s_setprio 1
	s_waitcnt lgkmcnt(0)
	v_mfma_f32_16x16x32_bf16 v[124:127], v[146:149], v[190:193], v[124:127]
	v_mfma_f32_16x16x32_bf16 v[120:123], v[154:157], v[190:193], v[120:123]
	v_mfma_f32_16x16x32_bf16 v[108:111], v[146:149], v[198:201], v[108:111]
	v_mfma_f32_16x16x32_bf16 v[104:107], v[154:157], v[198:201], v[104:107]
	v_mfma_f32_16x16x32_bf16 v[92:95], v[146:149], v[206:209], v[92:95]
	v_mfma_f32_16x16x32_bf16 v[88:91], v[154:157], v[206:209], v[88:91]
	v_mfma_f32_16x16x32_bf16 v[76:79], v[146:149], v[214:217], v[76:79]
	v_mfma_f32_16x16x32_bf16 v[72:75], v[154:157], v[214:217], v[72:75]
	v_mfma_f32_16x16x32_bf16 v[124:127], v[150:153], v[194:197], v[124:127]
	v_mfma_f32_16x16x32_bf16 v[120:123], v[166:169], v[194:197], v[120:123]
	v_mfma_f32_16x16x32_bf16 v[108:111], v[150:153], v[202:205], v[108:111]
	v_mfma_f32_16x16x32_bf16 v[104:107], v[166:169], v[202:205], v[104:107]
	v_mfma_f32_16x16x32_bf16 v[92:95], v[150:153], v[210:213], v[92:95]
	v_mfma_f32_16x16x32_bf16 v[88:91], v[166:169], v[210:213], v[88:91]
	v_mfma_f32_16x16x32_bf16 v[76:79], v[150:153], v[218:221], v[76:79]
	v_mfma_f32_16x16x32_bf16 v[72:75], v[166:169], v[218:221], v[72:75]
	s_setprio 0
	s_setprio 1
	v_mfma_f32_16x16x32_bf16 v[116:119], v[170:173], v[190:193], v[116:119]
	v_mfma_f32_16x16x32_bf16 v[112:115], v[178:181], v[190:193], v[112:115]
	v_mfma_f32_16x16x32_bf16 v[100:103], v[170:173], v[198:201], v[100:103]
	v_mfma_f32_16x16x32_bf16 v[96:99], v[178:181], v[198:201], v[96:99]
	v_mfma_f32_16x16x32_bf16 v[84:87], v[170:173], v[206:209], v[84:87]
	v_mfma_f32_16x16x32_bf16 v[80:83], v[178:181], v[206:209], v[80:83]
	v_mfma_f32_16x16x32_bf16 v[68:71], v[170:173], v[214:217], v[68:71]
	v_mfma_f32_16x16x32_bf16 v[64:67], v[178:181], v[214:217], v[64:67]
	v_mfma_f32_16x16x32_bf16 v[116:119], v[174:177], v[194:197], v[116:119]
	v_mfma_f32_16x16x32_bf16 v[112:115], v[182:185], v[194:197], v[112:115]
	v_mfma_f32_16x16x32_bf16 v[100:103], v[174:177], v[202:205], v[100:103]
	v_mfma_f32_16x16x32_bf16 v[96:99], v[182:185], v[202:205], v[96:99]
	v_mfma_f32_16x16x32_bf16 v[84:87], v[174:177], v[210:213], v[84:87]
	v_mfma_f32_16x16x32_bf16 v[80:83], v[182:185], v[210:213], v[80:83]
	v_mfma_f32_16x16x32_bf16 v[68:71], v[174:177], v[218:221], v[68:71]
	v_mfma_f32_16x16x32_bf16 v[64:67], v[182:185], v[218:221], v[64:67]
	s_setprio 0
	s_barrier
	s_add_i32 s34, s55, s33
	v_lshl_add_u64 v[158:159], v[158:159], 0, s[20:21]
	s_mov_b32 m0, s34
	ds_read_b128 v[190:193], v164 offset:49152
	ds_read_b128 v[194:197], v164 offset:50176
	ds_read_b128 v[198:201], v164 offset:51200
	ds_read_b128 v[202:205], v164 offset:52224
	ds_read_b128 v[206:209], v164 offset:53248
	ds_read_b128 v[210:213], v164 offset:54272
	ds_read_b128 v[214:217], v164 offset:55296
	ds_read_b128 v[218:221], v164 offset:56320
	global_load_lds_dwordx4 v[158:159], off
	s_add_i32 m0, s34, 0x2000
	s_add_u32 s8, s8, 0x40080
	v_lshl_add_u64 v[158:159], v[186:187], 0, s[20:21]
	s_addc_u32 s9, s9, 0
	s_add_i32 s34, s56, s33
	global_load_lds_dwordx4 v[158:159], off
	v_lshl_add_u64 v[158:159], s[8:9], 0, v[130:131]
	s_mov_b32 m0, s34
	s_nop 0
	global_load_lds_dwordx4 v[158:159], off
	v_lshl_add_u64 v[158:159], s[8:9], 0, v[134:135]
	s_add_i32 m0, s34, 0x2000
	s_nop 0
	global_load_lds_dwordx4 v[158:159], off
	v_lshl_add_u64 v[158:159], v[222:223], 0, s[20:21]
	s_mov_b32 m0, s40
	s_nop 0
	global_load_lds_dwordx4 v[158:159], off
	v_lshl_add_u64 v[158:159], v[224:225], 0, s[20:21]
	s_mov_b32 m0, s41
	s_nop 0
	global_load_lds_dwordx4 v[158:159], off
	s_waitcnt vmcnt(8)
	s_waitcnt lgkmcnt(0)
	s_barrier
	s_setprio 1
	s_waitcnt lgkmcnt(0)
	v_mfma_f32_16x16x32_bf16 v[60:63], v[146:149], v[190:193], v[60:63]
	v_mfma_f32_16x16x32_bf16 v[56:59], v[154:157], v[190:193], v[56:59]
	v_mfma_f32_16x16x32_bf16 v[44:47], v[146:149], v[198:201], v[44:47]
	v_mfma_f32_16x16x32_bf16 v[40:43], v[154:157], v[198:201], v[40:43]
	v_mfma_f32_16x16x32_bf16 v[28:31], v[146:149], v[206:209], v[28:31]
	v_mfma_f32_16x16x32_bf16 v[24:27], v[154:157], v[206:209], v[24:27]
	v_mfma_f32_16x16x32_bf16 v[12:15], v[146:149], v[214:217], v[12:15]
	v_mfma_f32_16x16x32_bf16 v[8:11], v[154:157], v[214:217], v[8:11]
	v_mfma_f32_16x16x32_bf16 v[60:63], v[150:153], v[194:197], v[60:63]
	v_mfma_f32_16x16x32_bf16 v[56:59], v[166:169], v[194:197], v[56:59]
	v_mfma_f32_16x16x32_bf16 v[44:47], v[150:153], v[202:205], v[44:47]
	v_mfma_f32_16x16x32_bf16 v[40:43], v[166:169], v[202:205], v[40:43]
	v_mfma_f32_16x16x32_bf16 v[28:31], v[150:153], v[210:213], v[28:31]
	v_mfma_f32_16x16x32_bf16 v[24:27], v[166:169], v[210:213], v[24:27]
	v_mfma_f32_16x16x32_bf16 v[12:15], v[150:153], v[218:221], v[12:15]
	v_mfma_f32_16x16x32_bf16 v[8:11], v[166:169], v[218:221], v[8:11]
	s_setprio 0
	s_setprio 1
	v_mfma_f32_16x16x32_bf16 v[52:55], v[170:173], v[190:193], v[52:55]
	v_mfma_f32_16x16x32_bf16 v[48:51], v[178:181], v[190:193], v[48:51]
	v_mfma_f32_16x16x32_bf16 v[36:39], v[170:173], v[198:201], v[36:39]
	v_mfma_f32_16x16x32_bf16 v[32:35], v[178:181], v[198:201], v[32:35]
	v_mfma_f32_16x16x32_bf16 v[20:23], v[170:173], v[206:209], v[20:23]
	v_mfma_f32_16x16x32_bf16 v[16:19], v[178:181], v[206:209], v[16:19]
	v_mfma_f32_16x16x32_bf16 v[4:7], v[170:173], v[214:217], v[4:7]
	v_mfma_f32_16x16x32_bf16 v[0:3], v[178:181], v[214:217], v[0:3]
	v_mfma_f32_16x16x32_bf16 v[52:55], v[174:177], v[194:197], v[52:55]
	v_mfma_f32_16x16x32_bf16 v[48:51], v[182:185], v[194:197], v[48:51]
	v_mfma_f32_16x16x32_bf16 v[36:39], v[174:177], v[202:205], v[36:39]
	v_mfma_f32_16x16x32_bf16 v[32:35], v[182:185], v[202:205], v[32:35]
	v_mfma_f32_16x16x32_bf16 v[20:23], v[174:177], v[210:213], v[20:23]
	v_mfma_f32_16x16x32_bf16 v[16:19], v[182:185], v[210:213], v[16:19]
	v_mfma_f32_16x16x32_bf16 v[4:7], v[174:177], v[218:221], v[4:7]
	v_mfma_f32_16x16x32_bf16 v[0:3], v[182:185], v[218:221], v[0:3]
	s_setprio 0
	s_add_i32 s54, s54, 2
	s_add_u32 s6, s6, 0x100
	s_addc_u32 s7, s7, 0
	s_add_u32 s27, s27, 0x100
	s_addc_u32 s53, s53, 0
	s_cmp_gt_u32 s54, 13
	s_barrier
	s_cbranch_scc0 .LBB0_88
	s_and_b64 vcc, exec, s[22:23]
	s_cbranch_vccz .LBB0_91
	s_barrier

.LBB0_630:
	v_add_u32_e32 v1, s47, v158
	ds_read_b128 v[174:177], v1
	ds_read_b128 v[178:181], v1 offset:1024
	ds_read_b128 v[182:185], v1 offset:2048
	ds_read_b128 v[190:193], v1 offset:3072
	v_add_u32_e32 v1, s48, v158
	s_add_u32 s53, s58, s54
	ds_read_b128 v[194:197], v1
	ds_read_b128 v[198:201], v1 offset:1024
	ds_read_b128 v[202:205], v1 offset:2048
	ds_read_b128 v[206:209], v1 offset:3072
	s_addc_u32 s57, s59, s55
	s_add_u32 s53, s53, 0x100
	s_addc_u32 s57, s57, 0
	s_add_u32 s60, s50, s54
	s_addc_u32 s61, s51, s55
	s_cmpk_eq_i32 s54, 0x700
	s_cselect_b32 s63, s21, s57
	s_cselect_b32 s62, s26, s53
	s_cselect_b32 s61, s19, s61
	s_cselect_b32 s60, s27, s60
	v_lshl_add_u64 v[2:3], v[148:149], 0, s[54:55]
	s_add_i32 m0, s38, 0xc000
	ds_read_b128 v[210:213], v169
	ds_read_b128 v[214:217], v169 offset:1024
	ds_read_b128 v[218:221], v169 offset:2048
	ds_read_b128 v[222:225], v169 offset:3072
	ds_read_b128 v[226:229], v169 offset:4096
	ds_read_b128 v[230:233], v169 offset:5120
	ds_read_b128 v[234:237], v169 offset:6144
	ds_read_b128 v[238:241], v169 offset:7168
	global_load_lds_dwordx4 v[2:3], off
	v_lshl_add_u64 v[2:3], v[150:151], 0, s[54:55]
	s_add_i32 m0, s38, 0xe000
	s_nop 0
	global_load_lds_dwordx4 v[2:3], off
	s_waitcnt vmcnt(8)
	s_waitcnt lgkmcnt(0)
	s_barrier
	s_setprio 1
	s_waitcnt lgkmcnt(0)
	v_mfma_f32_16x16x32_bf16 v[128:131], v[174:177], v[210:213], v[128:131]
	v_mfma_f32_16x16x32_bf16 v[124:127], v[182:185], v[210:213], v[124:127]
	v_mfma_f32_16x16x32_bf16 v[112:115], v[174:177], v[218:221], v[112:115]
	v_mfma_f32_16x16x32_bf16 v[108:111], v[182:185], v[218:221], v[108:111]
	v_mfma_f32_16x16x32_bf16 v[96:99], v[174:177], v[226:229], v[96:99]
	v_mfma_f32_16x16x32_bf16 v[92:95], v[182:185], v[226:229], v[92:95]
	v_mfma_f32_16x16x32_bf16 v[80:83], v[174:177], v[234:237], v[80:83]
	v_mfma_f32_16x16x32_bf16 v[76:79], v[182:185], v[234:237], v[76:79]
	v_mfma_f32_16x16x32_bf16 v[128:131], v[178:181], v[214:217], v[128:131]
	v_mfma_f32_16x16x32_bf16 v[124:127], v[190:193], v[214:217], v[124:127]
	v_mfma_f32_16x16x32_bf16 v[112:115], v[178:181], v[222:225], v[112:115]
	v_mfma_f32_16x16x32_bf16 v[108:111], v[190:193], v[222:225], v[108:111]
	v_mfma_f32_16x16x32_bf16 v[96:99], v[178:181], v[230:233], v[96:99]
	v_mfma_f32_16x16x32_bf16 v[92:95], v[190:193], v[230:233], v[92:95]
	v_mfma_f32_16x16x32_bf16 v[80:83], v[178:181], v[238:241], v[80:83]
	v_mfma_f32_16x16x32_bf16 v[76:79], v[190:193], v[238:241], v[76:79]
	s_setprio 0
	s_setprio 1
	v_mfma_f32_16x16x32_bf16 v[120:123], v[194:197], v[210:213], v[120:123]
	v_mfma_f32_16x16x32_bf16 v[116:119], v[202:205], v[210:213], v[116:119]
	v_mfma_f32_16x16x32_bf16 v[104:107], v[194:197], v[218:221], v[104:107]
	v_mfma_f32_16x16x32_bf16 v[100:103], v[202:205], v[218:221], v[100:103]
	v_mfma_f32_16x16x32_bf16 v[88:91], v[194:197], v[226:229], v[88:91]
	v_mfma_f32_16x16x32_bf16 v[84:87], v[202:205], v[226:229], v[84:87]
	v_mfma_f32_16x16x32_bf16 v[72:75], v[194:197], v[234:237], v[72:75]
	v_mfma_f32_16x16x32_bf16 v[68:71], v[202:205], v[234:237], v[68:71]
	v_mfma_f32_16x16x32_bf16 v[120:123], v[198:201], v[214:217], v[120:123]
	v_mfma_f32_16x16x32_bf16 v[116:119], v[206:209], v[214:217], v[116:119]
	v_mfma_f32_16x16x32_bf16 v[104:107], v[198:201], v[222:225], v[104:107]
	v_mfma_f32_16x16x32_bf16 v[100:103], v[206:209], v[222:225], v[100:103]
	v_mfma_f32_16x16x32_bf16 v[88:91], v[198:201], v[230:233], v[88:91]
	v_mfma_f32_16x16x32_bf16 v[84:87], v[206:209], v[230:233], v[84:87]
	v_mfma_f32_16x16x32_bf16 v[72:75], v[198:201], v[238:241], v[72:75]
	v_mfma_f32_16x16x32_bf16 v[68:71], v[206:209], v[238:241], v[68:71]
	s_setprio 0
	s_barrier
	s_add_i32 s53, s47, s33
	v_lshl_add_u64 v[186:187], s[60:61], 0, v[134:135]
	s_mov_b32 m0, s53
	ds_read_b128 v[210:213], v169 offset:16384
	ds_read_b128 v[214:217], v169 offset:17408
	ds_read_b128 v[218:221], v169 offset:18432
	ds_read_b128 v[222:225], v169 offset:19456
	ds_read_b128 v[226:229], v169 offset:20480
	ds_read_b128 v[230:233], v169 offset:21504
	ds_read_b128 v[234:237], v169 offset:22528
	ds_read_b128 v[238:241], v169 offset:23552
	global_load_lds_dwordx4 v[186:187], off
	s_add_i32 m0, s53, 0x2000
	s_add_u32 s64, s60, 0x40000
	v_lshl_add_u64 v[242:243], s[60:61], 0, v[138:139]
	s_addc_u32 s65, s61, 0
	s_add_i32 s53, s48, s33
	global_load_lds_dwordx4 v[242:243], off
	v_lshl_add_u64 v[2:3], s[64:65], 0, v[134:135]
	s_mov_b32 m0, s53
	v_lshl_add_u64 v[244:245], s[62:63], 0, v[132:133]
	global_load_lds_dwordx4 v[2:3], off
	v_lshl_add_u64 v[2:3], s[64:65], 0, v[138:139]
	s_add_i32 m0, s53, 0x2000
	v_lshl_add_u64 v[246:247], s[62:63], 0, v[136:137]
	global_load_lds_dwordx4 v[2:3], off
	s_mov_b32 m0, s38
	s_nop 0
	global_load_lds_dwordx4 v[244:245], off
	s_mov_b32 m0, s39
	s_nop 0
	global_load_lds_dwordx4 v[246:247], off
	s_waitcnt vmcnt(8)
	s_waitcnt lgkmcnt(0)
	s_barrier
	s_setprio 1
	s_waitcnt lgkmcnt(0)
	v_mfma_f32_16x16x32_bf16 v[64:67], v[174:177], v[210:213], v[64:67]
	v_mfma_f32_16x16x32_bf16 v[60:63], v[182:185], v[210:213], v[60:63]
	v_mfma_f32_16x16x32_bf16 v[48:51], v[174:177], v[218:221], v[48:51]
	v_mfma_f32_16x16x32_bf16 v[44:47], v[182:185], v[218:221], v[44:47]
	v_mfma_f32_16x16x32_bf16 v[32:35], v[174:177], v[226:229], v[32:35]
	v_mfma_f32_16x16x32_bf16 v[28:31], v[182:185], v[226:229], v[28:31]
	v_mfma_f32_16x16x32_bf16 v[16:19], v[174:177], v[234:237], v[16:19]
	v_mfma_f32_16x16x32_bf16 v[12:15], v[182:185], v[234:237], v[12:15]
	v_mfma_f32_16x16x32_bf16 v[64:67], v[178:181], v[214:217], v[64:67]
	v_mfma_f32_16x16x32_bf16 v[60:63], v[190:193], v[214:217], v[60:63]
	v_mfma_f32_16x16x32_bf16 v[48:51], v[178:181], v[222:225], v[48:51]
	v_mfma_f32_16x16x32_bf16 v[44:47], v[190:193], v[222:225], v[44:47]
	v_mfma_f32_16x16x32_bf16 v[32:35], v[178:181], v[230:233], v[32:35]
	v_mfma_f32_16x16x32_bf16 v[28:31], v[190:193], v[230:233], v[28:31]
	v_mfma_f32_16x16x32_bf16 v[16:19], v[178:181], v[238:241], v[16:19]
	v_mfma_f32_16x16x32_bf16 v[12:15], v[190:193], v[238:241], v[12:15]
	s_setprio 0
	s_setprio 1
	v_mfma_f32_16x16x32_bf16 v[56:59], v[194:197], v[210:213], v[56:59]
	v_mfma_f32_16x16x32_bf16 v[52:55], v[202:205], v[210:213], v[52:55]
	v_mfma_f32_16x16x32_bf16 v[40:43], v[194:197], v[218:221], v[40:43]
	v_mfma_f32_16x16x32_bf16 v[36:39], v[202:205], v[218:221], v[36:39]
	v_mfma_f32_16x16x32_bf16 v[24:27], v[194:197], v[226:229], v[24:27]
	v_mfma_f32_16x16x32_bf16 v[20:23], v[202:205], v[226:229], v[20:23]
	v_mfma_f32_16x16x32_bf16 v[8:11], v[194:197], v[234:237], v[8:11]
	v_mfma_f32_16x16x32_bf16 v[2:5], v[202:205], v[234:237], v[4:7]
	v_mfma_f32_16x16x32_bf16 v[56:59], v[198:201], v[214:217], v[56:59]
	v_mfma_f32_16x16x32_bf16 v[52:55], v[206:209], v[214:217], v[52:55]
	v_mfma_f32_16x16x32_bf16 v[40:43], v[198:201], v[222:225], v[40:43]
	v_mfma_f32_16x16x32_bf16 v[36:39], v[206:209], v[222:225], v[36:39]
	v_mfma_f32_16x16x32_bf16 v[24:27], v[198:201], v[230:233], v[24:27]
	v_mfma_f32_16x16x32_bf16 v[20:23], v[206:209], v[230:233], v[20:23]
	v_mfma_f32_16x16x32_bf16 v[8:11], v[198:201], v[238:241], v[8:11]
	v_mfma_f32_16x16x32_bf16 v[2:5], v[206:209], v[238:241], v[2:5]
	s_setprio 0
	s_barrier
	s_add_i32 s53, 0, 0x18000
	v_add_u32_e32 v1, s53, v158
	s_add_i32 s57, 0, 0x1c000
	ds_read_b128 v[174:177], v1
	ds_read_b128 v[178:181], v1 offset:1024
	ds_read_b128 v[182:185], v1 offset:2048
	ds_read_b128 v[190:193], v1 offset:3072
	v_add_u32_e32 v1, s57, v158
	ds_read_b128 v[194:197], v1
	ds_read_b128 v[198:201], v1 offset:1024
	ds_read_b128 v[202:205], v1 offset:2048
	ds_read_b128 v[206:209], v1 offset:3072
	s_add_u32 s62, s62, 0x40000
	s_addc_u32 s63, s63, 0
	s_mov_b32 m0, s40
	v_lshl_add_u64 v[6:7], s[62:63], 0, v[132:133]
	ds_read_b128 v[210:213], v169 offset:32768
	ds_read_b128 v[214:217], v169 offset:33792
	ds_read_b128 v[218:221], v169 offset:34816
	ds_read_b128 v[222:225], v169 offset:35840
	ds_read_b128 v[226:229], v169 offset:36864
	ds_read_b128 v[230:233], v169 offset:37888
	ds_read_b128 v[234:237], v169 offset:38912
	ds_read_b128 v[238:241], v169 offset:39936
	global_load_lds_dwordx4 v[6:7], off
	v_lshl_add_u64 v[6:7], s[62:63], 0, v[136:137]
	s_mov_b32 m0, s41
	s_nop 0
	global_load_lds_dwordx4 v[6:7], off
	s_waitcnt vmcnt(8)
	s_waitcnt lgkmcnt(0)
	s_barrier
	s_setprio 1
	s_waitcnt lgkmcnt(0)
	v_mfma_f32_16x16x32_bf16 v[128:131], v[174:177], v[210:213], v[128:131]
	v_mfma_f32_16x16x32_bf16 v[124:127], v[182:185], v[210:213], v[124:127]
	v_mfma_f32_16x16x32_bf16 v[112:115], v[174:177], v[218:221], v[112:115]
	v_mfma_f32_16x16x32_bf16 v[108:111], v[182:185], v[218:221], v[108:111]
	v_mfma_f32_16x16x32_bf16 v[96:99], v[174:177], v[226:229], v[96:99]
	v_mfma_f32_16x16x32_bf16 v[92:95], v[182:185], v[226:229], v[92:95]
	v_mfma_f32_16x16x32_bf16 v[80:83], v[174:177], v[234:237], v[80:83]
	v_mfma_f32_16x16x32_bf16 v[76:79], v[182:185], v[234:237], v[76:79]
	v_mfma_f32_16x16x32_bf16 v[128:131], v[178:181], v[214:217], v[128:131]
	v_mfma_f32_16x16x32_bf16 v[124:127], v[190:193], v[214:217], v[124:127]
	v_mfma_f32_16x16x32_bf16 v[112:115], v[178:181], v[222:225], v[112:115]
	v_mfma_f32_16x16x32_bf16 v[108:111], v[190:193], v[222:225], v[108:111]
	v_mfma_f32_16x16x32_bf16 v[96:99], v[178:181], v[230:233], v[96:99]
	v_mfma_f32_16x16x32_bf16 v[92:95], v[190:193], v[230:233], v[92:95]
	v_mfma_f32_16x16x32_bf16 v[80:83], v[178:181], v[238:241], v[80:83]
	v_mfma_f32_16x16x32_bf16 v[76:79], v[190:193], v[238:241], v[76:79]
	s_setprio 0
	s_setprio 1
	v_mfma_f32_16x16x32_bf16 v[120:123], v[194:197], v[210:213], v[120:123]
	v_mfma_f32_16x16x32_bf16 v[116:119], v[202:205], v[210:213], v[116:119]
	v_mfma_f32_16x16x32_bf16 v[104:107], v[194:197], v[218:221], v[104:107]
	v_mfma_f32_16x16x32_bf16 v[100:103], v[202:205], v[218:221], v[100:103]
	v_mfma_f32_16x16x32_bf16 v[88:91], v[194:197], v[226:229], v[88:91]
	v_mfma_f32_16x16x32_bf16 v[84:87], v[202:205], v[226:229], v[84:87]
	v_mfma_f32_16x16x32_bf16 v[72:75], v[194:197], v[234:237], v[72:75]
	v_mfma_f32_16x16x32_bf16 v[68:71], v[202:205], v[234:237], v[68:71]
	v_mfma_f32_16x16x32_bf16 v[120:123], v[198:201], v[214:217], v[120:123]
	v_mfma_f32_16x16x32_bf16 v[116:119], v[206:209], v[214:217], v[116:119]
	v_mfma_f32_16x16x32_bf16 v[104:107], v[198:201], v[222:225], v[104:107]
	v_mfma_f32_16x16x32_bf16 v[100:103], v[206:209], v[222:225], v[100:103]
	v_mfma_f32_16x16x32_bf16 v[88:91], v[198:201], v[230:233], v[88:91]
	v_mfma_f32_16x16x32_bf16 v[84:87], v[206:209], v[230:233], v[84:87]
	v_mfma_f32_16x16x32_bf16 v[72:75], v[198:201], v[238:241], v[72:75]
	v_mfma_f32_16x16x32_bf16 v[68:71], v[206:209], v[238:241], v[68:71]
	s_setprio 0
	s_barrier
	s_add_i32 s53, s53, s33
	v_lshl_add_u64 v[6:7], v[186:187], 0, s[14:15]
	s_mov_b32 m0, s53
	ds_read_b128 v[210:213], v169 offset:49152
	ds_read_b128 v[214:217], v169 offset:50176
	ds_read_b128 v[218:221], v169 offset:51200
	ds_read_b128 v[222:225], v169 offset:52224
	ds_read_b128 v[226:229], v169 offset:53248
	ds_read_b128 v[230:233], v169 offset:54272
	ds_read_b128 v[234:237], v169 offset:55296
	ds_read_b128 v[238:241], v169 offset:56320
	global_load_lds_dwordx4 v[6:7], off
	s_add_i32 m0, s53, 0x2000
	s_add_u32 s60, s60, 0x40080
	v_lshl_add_u64 v[6:7], v[242:243], 0, s[14:15]
	s_addc_u32 s61, s61, 0
	s_add_i32 s53, s57, s33
	global_load_lds_dwordx4 v[6:7], off
	v_lshl_add_u64 v[6:7], s[60:61], 0, v[134:135]
	s_mov_b32 m0, s53
	s_nop 0
	global_load_lds_dwordx4 v[6:7], off
	v_lshl_add_u64 v[6:7], s[60:61], 0, v[138:139]
	s_add_i32 m0, s53, 0x2000
	s_nop 0
	global_load_lds_dwordx4 v[6:7], off
	v_lshl_add_u64 v[6:7], v[244:245], 0, s[14:15]
	s_mov_b32 m0, s42
	s_nop 0
	global_load_lds_dwordx4 v[6:7], off
	v_lshl_add_u64 v[6:7], v[246:247], 0, s[14:15]
	s_mov_b32 m0, s43
	s_nop 0
	global_load_lds_dwordx4 v[6:7], off
	s_waitcnt vmcnt(8)
	s_waitcnt lgkmcnt(0)
	s_barrier
	s_setprio 1
	s_waitcnt lgkmcnt(0)
	v_mfma_f32_16x16x32_bf16 v[64:67], v[174:177], v[210:213], v[64:67]
	v_mfma_f32_16x16x32_bf16 v[60:63], v[182:185], v[210:213], v[60:63]
	v_mfma_f32_16x16x32_bf16 v[48:51], v[174:177], v[218:221], v[48:51]
	v_mfma_f32_16x16x32_bf16 v[44:47], v[182:185], v[218:221], v[44:47]
	v_mfma_f32_16x16x32_bf16 v[32:35], v[174:177], v[226:229], v[32:35]
	v_mfma_f32_16x16x32_bf16 v[28:31], v[182:185], v[226:229], v[28:31]
	v_mfma_f32_16x16x32_bf16 v[16:19], v[174:177], v[234:237], v[16:19]
	v_mfma_f32_16x16x32_bf16 v[12:15], v[182:185], v[234:237], v[12:15]
	v_mfma_f32_16x16x32_bf16 v[64:67], v[178:181], v[214:217], v[64:67]
	v_mfma_f32_16x16x32_bf16 v[60:63], v[190:193], v[214:217], v[60:63]
	v_mfma_f32_16x16x32_bf16 v[48:51], v[178:181], v[222:225], v[48:51]
	v_mfma_f32_16x16x32_bf16 v[44:47], v[190:193], v[222:225], v[44:47]
	v_mfma_f32_16x16x32_bf16 v[32:35], v[178:181], v[230:233], v[32:35]
	v_mfma_f32_16x16x32_bf16 v[28:31], v[190:193], v[230:233], v[28:31]
	v_mfma_f32_16x16x32_bf16 v[16:19], v[178:181], v[238:241], v[16:19]
	v_mfma_f32_16x16x32_bf16 v[12:15], v[190:193], v[238:241], v[12:15]
	s_setprio 0
	s_setprio 1
	v_mfma_f32_16x16x32_bf16 v[56:59], v[194:197], v[210:213], v[56:59]
	v_mfma_f32_16x16x32_bf16 v[52:55], v[202:205], v[210:213], v[52:55]
	v_mfma_f32_16x16x32_bf16 v[40:43], v[194:197], v[218:221], v[40:43]
	v_mfma_f32_16x16x32_bf16 v[36:39], v[202:205], v[218:221], v[36:39]
	v_mfma_f32_16x16x32_bf16 v[24:27], v[194:197], v[226:229], v[24:27]
	v_mfma_f32_16x16x32_bf16 v[20:23], v[202:205], v[226:229], v[20:23]
	v_mfma_f32_16x16x32_bf16 v[6:9], v[194:197], v[234:237], v[8:11]
	v_mfma_f32_16x16x32_bf16 v[2:5], v[202:205], v[234:237], v[2:5]
	v_mfma_f32_16x16x32_bf16 v[56:59], v[198:201], v[214:217], v[56:59]
	v_mfma_f32_16x16x32_bf16 v[52:55], v[206:209], v[214:217], v[52:55]
	v_mfma_f32_16x16x32_bf16 v[40:43], v[198:201], v[222:225], v[40:43]
	v_mfma_f32_16x16x32_bf16 v[36:39], v[206:209], v[222:225], v[36:39]
	v_mfma_f32_16x16x32_bf16 v[24:27], v[198:201], v[230:233], v[24:27]
	v_mfma_f32_16x16x32_bf16 v[20:23], v[206:209], v[230:233], v[20:23]
	v_mfma_f32_16x16x32_bf16 v[8:11], v[198:201], v[238:241], v[6:9]
	v_mfma_f32_16x16x32_bf16 v[4:7], v[206:209], v[238:241], v[2:5]
	s_setprio 0
	s_add_i32 s52, s52, 2
	s_add_u32 s54, s54, 0x100
	s_addc_u32 s55, s55, 0
	s_cmp_gt_u32 s52, 13
	s_barrier
	s_cbranch_scc1 .LBB0_633

.LBB0_980:
	ds_read_b128 v[144:147], v151
	ds_read_b128 v[156:159], v151 offset:1024
	ds_read_b128 v[160:163], v151 offset:2048
	ds_read_b128 v[164:167], v151 offset:3072
	ds_read_b128 v[168:171], v152
	ds_read_b128 v[172:175], v152 offset:1024
	ds_read_b128 v[176:179], v152 offset:2048
	ds_read_b128 v[180:183], v152 offset:3072
	s_add_u32 s34, s22, 0xfffc0080
	s_addc_u32 s35, s23, -1
	s_cmp_eq_u32 s55, 12
	s_cselect_b32 s37, s15, s35
	s_cselect_b32 s36, s51, s34
	s_cselect_b32 s35, s13, s54
	s_cselect_b32 s34, s52, s53
	v_lshl_add_u64 v[218:219], s[22:23], 0, v[136:137]
	s_add_i32 m0, s21, 0xc000
	ds_read_b128 v[184:187], v153
	ds_read_b128 v[190:193], v153 offset:1024
	ds_read_b128 v[194:197], v153 offset:2048
	ds_read_b128 v[198:201], v153 offset:3072
	ds_read_b128 v[202:205], v153 offset:4096
	ds_read_b128 v[206:209], v153 offset:5120
	ds_read_b128 v[210:213], v153 offset:6144
	ds_read_b128 v[214:217], v153 offset:7168
	global_load_lds_dwordx4 v[218:219], off
	v_lshl_add_u64 v[218:219], s[22:23], 0, v[138:139]
	s_add_i32 m0, s21, 0xe000
	s_nop 0
	global_load_lds_dwordx4 v[218:219], off
	s_waitcnt vmcnt(8)
	s_waitcnt lgkmcnt(0)
	s_barrier
	s_setprio 1
	s_waitcnt lgkmcnt(0)
	v_mfma_f32_16x16x32_bf16 v[116:119], v[144:147], v[184:187], v[116:119]
	v_mfma_f32_16x16x32_bf16 v[112:115], v[160:163], v[184:187], v[112:115]
	v_mfma_f32_16x16x32_bf16 v[104:107], v[144:147], v[194:197], v[104:107]
	v_mfma_f32_16x16x32_bf16 v[96:99], v[160:163], v[194:197], v[96:99]
	v_mfma_f32_16x16x32_bf16 v[88:91], v[144:147], v[202:205], v[88:91]
	v_mfma_f32_16x16x32_bf16 v[80:83], v[160:163], v[202:205], v[80:83]
	v_mfma_f32_16x16x32_bf16 v[72:75], v[144:147], v[210:213], v[72:75]
	v_mfma_f32_16x16x32_bf16 v[68:71], v[160:163], v[210:213], v[68:71]
	v_mfma_f32_16x16x32_bf16 v[116:119], v[156:159], v[190:193], v[116:119]
	v_mfma_f32_16x16x32_bf16 v[112:115], v[164:167], v[190:193], v[112:115]
	v_mfma_f32_16x16x32_bf16 v[104:107], v[156:159], v[198:201], v[104:107]
	v_mfma_f32_16x16x32_bf16 v[96:99], v[164:167], v[198:201], v[96:99]
	v_mfma_f32_16x16x32_bf16 v[88:91], v[156:159], v[206:209], v[88:91]
	v_mfma_f32_16x16x32_bf16 v[80:83], v[164:167], v[206:209], v[80:83]
	v_mfma_f32_16x16x32_bf16 v[72:75], v[156:159], v[214:217], v[72:75]
	v_mfma_f32_16x16x32_bf16 v[68:71], v[164:167], v[214:217], v[68:71]
	s_setprio 0
	s_setprio 1
	v_mfma_f32_16x16x32_bf16 v[124:127], v[168:171], v[184:187], v[124:127]
	v_mfma_f32_16x16x32_bf16 v[120:123], v[176:179], v[184:187], v[120:123]
	v_mfma_f32_16x16x32_bf16 v[108:111], v[168:171], v[194:197], v[108:111]
	v_mfma_f32_16x16x32_bf16 v[100:103], v[176:179], v[194:197], v[100:103]
	v_mfma_f32_16x16x32_bf16 v[92:95], v[168:171], v[202:205], v[92:95]
	v_mfma_f32_16x16x32_bf16 v[84:87], v[176:179], v[202:205], v[84:87]
	v_mfma_f32_16x16x32_bf16 v[76:79], v[168:171], v[210:213], v[76:79]
	v_mfma_f32_16x16x32_bf16 v[64:67], v[176:179], v[210:213], v[64:67]
	v_mfma_f32_16x16x32_bf16 v[124:127], v[172:175], v[190:193], v[124:127]
	v_mfma_f32_16x16x32_bf16 v[120:123], v[180:183], v[190:193], v[120:123]
	v_mfma_f32_16x16x32_bf16 v[108:111], v[172:175], v[198:201], v[108:111]
	v_mfma_f32_16x16x32_bf16 v[100:103], v[180:183], v[198:201], v[100:103]
	v_mfma_f32_16x16x32_bf16 v[92:95], v[172:175], v[206:209], v[92:95]
	v_mfma_f32_16x16x32_bf16 v[84:87], v[180:183], v[206:209], v[84:87]
	v_mfma_f32_16x16x32_bf16 v[76:79], v[172:175], v[214:217], v[76:79]
	v_mfma_f32_16x16x32_bf16 v[64:67], v[180:183], v[214:217], v[64:67]
	s_setprio 0
	s_barrier
	s_add_i32 s56, s47, s38
	v_lshl_add_u64 v[218:219], s[34:35], 0, v[130:131]
	s_mov_b32 m0, s56
	ds_read_b128 v[184:187], v153 offset:16384
	ds_read_b128 v[190:193], v153 offset:17408
	ds_read_b128 v[194:197], v153 offset:18432
	ds_read_b128 v[198:201], v153 offset:19456
	ds_read_b128 v[202:205], v153 offset:20480
	ds_read_b128 v[206:209], v153 offset:21504
	ds_read_b128 v[210:213], v153 offset:22528
	ds_read_b128 v[214:217], v153 offset:23552
	global_load_lds_dwordx4 v[218:219], off
	s_add_i32 m0, s56, 0x2000
	s_add_u32 s56, s34, 0x40000
	v_lshl_add_u64 v[220:221], s[34:35], 0, v[134:135]
	s_addc_u32 s57, s35, 0
	s_add_i32 s58, s48, s38
	global_load_lds_dwordx4 v[220:221], off
	v_lshl_add_u64 v[222:223], s[56:57], 0, v[130:131]
	s_mov_b32 m0, s58
	v_lshl_add_u64 v[224:225], s[36:37], 0, v[132:133]
	global_load_lds_dwordx4 v[222:223], off
	v_lshl_add_u64 v[222:223], s[56:57], 0, v[134:135]
	s_add_i32 m0, s58, 0x2000
	s_nop 0
	global_load_lds_dwordx4 v[222:223], off
	v_lshl_add_u64 v[222:223], s[36:37], 0, v[128:129]
	s_mov_b32 m0, s21
	s_nop 0
	global_load_lds_dwordx4 v[222:223], off
	s_mov_b32 m0, s39
	s_nop 0
	global_load_lds_dwordx4 v[224:225], off
	s_waitcnt vmcnt(8)
	s_waitcnt lgkmcnt(0)
	s_barrier
	s_setprio 1
	s_waitcnt lgkmcnt(0)
	v_mfma_f32_16x16x32_bf16 v[56:59], v[144:147], v[184:187], v[56:59]
	v_mfma_f32_16x16x32_bf16 v[48:51], v[160:163], v[184:187], v[48:51]
	v_mfma_f32_16x16x32_bf16 v[40:43], v[144:147], v[194:197], v[40:43]
	v_mfma_f32_16x16x32_bf16 v[32:35], v[160:163], v[194:197], v[32:35]
	v_mfma_f32_16x16x32_bf16 v[24:27], v[144:147], v[202:205], v[24:27]
	v_mfma_f32_16x16x32_bf16 v[16:19], v[160:163], v[202:205], v[16:19]
	v_mfma_f32_16x16x32_bf16 v[8:11], v[144:147], v[210:213], v[8:11]
	v_mfma_f32_16x16x32_bf16 v[0:3], v[160:163], v[210:213], v[0:3]
	v_mfma_f32_16x16x32_bf16 v[56:59], v[156:159], v[190:193], v[56:59]
	v_mfma_f32_16x16x32_bf16 v[48:51], v[164:167], v[190:193], v[48:51]
	v_mfma_f32_16x16x32_bf16 v[40:43], v[156:159], v[198:201], v[40:43]
	v_mfma_f32_16x16x32_bf16 v[32:35], v[164:167], v[198:201], v[32:35]
	v_mfma_f32_16x16x32_bf16 v[24:27], v[156:159], v[206:209], v[24:27]
	v_mfma_f32_16x16x32_bf16 v[16:19], v[164:167], v[206:209], v[16:19]
	v_mfma_f32_16x16x32_bf16 v[8:11], v[156:159], v[214:217], v[8:11]
	v_mfma_f32_16x16x32_bf16 v[0:3], v[164:167], v[214:217], v[0:3]
	s_setprio 0
	s_setprio 1
	v_mfma_f32_16x16x32_bf16 v[60:63], v[168:171], v[184:187], v[60:63]
	v_mfma_f32_16x16x32_bf16 v[52:55], v[176:179], v[184:187], v[52:55]
	v_mfma_f32_16x16x32_bf16 v[44:47], v[168:171], v[194:197], v[44:47]
	v_mfma_f32_16x16x32_bf16 v[36:39], v[176:179], v[194:197], v[36:39]
	v_mfma_f32_16x16x32_bf16 v[28:31], v[168:171], v[202:205], v[28:31]
	v_mfma_f32_16x16x32_bf16 v[20:23], v[176:179], v[202:205], v[20:23]
	v_mfma_f32_16x16x32_bf16 v[12:15], v[168:171], v[210:213], v[12:15]
	v_mfma_f32_16x16x32_bf16 v[4:7], v[176:179], v[210:213], v[4:7]
	v_mfma_f32_16x16x32_bf16 v[60:63], v[172:175], v[190:193], v[60:63]
	v_mfma_f32_16x16x32_bf16 v[52:55], v[180:183], v[190:193], v[52:55]
	v_mfma_f32_16x16x32_bf16 v[44:47], v[172:175], v[198:201], v[44:47]
	v_mfma_f32_16x16x32_bf16 v[36:39], v[180:183], v[198:201], v[36:39]
	v_mfma_f32_16x16x32_bf16 v[28:31], v[172:175], v[206:209], v[28:31]
	v_mfma_f32_16x16x32_bf16 v[20:23], v[180:183], v[206:209], v[20:23]
	v_mfma_f32_16x16x32_bf16 v[12:15], v[172:175], v[214:217], v[12:15]
	v_mfma_f32_16x16x32_bf16 v[4:7], v[180:183], v[214:217], v[4:7]
	s_setprio 0
	s_barrier
	s_add_i32 s56, 0, 0x18000
	v_add_u32_e32 v155, s56, v149
	s_add_i32 s57, 0, 0x1c000
	ds_read_b128 v[144:147], v155
	ds_read_b128 v[156:159], v155 offset:1024
	ds_read_b128 v[160:163], v155 offset:2048
	ds_read_b128 v[164:167], v155 offset:3072
	v_add_u32_e32 v155, s57, v149
	ds_read_b128 v[168:171], v155
	ds_read_b128 v[172:175], v155 offset:1024
	ds_read_b128 v[176:179], v155 offset:2048
	ds_read_b128 v[180:183], v155 offset:3072
	s_add_u32 s36, s36, 0x40000
	s_addc_u32 s37, s37, 0
	s_mov_b32 m0, s40
	v_lshl_add_u64 v[226:227], s[36:37], 0, v[128:129]
	ds_read_b128 v[184:187], v153 offset:32768
	ds_read_b128 v[190:193], v153 offset:33792
	ds_read_b128 v[194:197], v153 offset:34816
	ds_read_b128 v[198:201], v153 offset:35840
	ds_read_b128 v[202:205], v153 offset:36864
	ds_read_b128 v[206:209], v153 offset:37888
	ds_read_b128 v[210:213], v153 offset:38912
	ds_read_b128 v[214:217], v153 offset:39936
	global_load_lds_dwordx4 v[226:227], off
	v_lshl_add_u64 v[226:227], s[36:37], 0, v[132:133]
	s_mov_b32 m0, s41
	s_nop 0
	global_load_lds_dwordx4 v[226:227], off
	s_waitcnt vmcnt(8)
	s_waitcnt lgkmcnt(0)
	s_barrier
	s_setprio 1
	s_waitcnt lgkmcnt(0)
	v_mfma_f32_16x16x32_bf16 v[116:119], v[144:147], v[184:187], v[116:119]
	v_mfma_f32_16x16x32_bf16 v[112:115], v[160:163], v[184:187], v[112:115]
	v_mfma_f32_16x16x32_bf16 v[104:107], v[144:147], v[194:197], v[104:107]
	v_mfma_f32_16x16x32_bf16 v[96:99], v[160:163], v[194:197], v[96:99]
	v_mfma_f32_16x16x32_bf16 v[88:91], v[144:147], v[202:205], v[88:91]
	v_mfma_f32_16x16x32_bf16 v[80:83], v[160:163], v[202:205], v[80:83]
	v_mfma_f32_16x16x32_bf16 v[72:75], v[144:147], v[210:213], v[72:75]
	v_mfma_f32_16x16x32_bf16 v[68:71], v[160:163], v[210:213], v[68:71]
	v_mfma_f32_16x16x32_bf16 v[116:119], v[156:159], v[190:193], v[116:119]
	v_mfma_f32_16x16x32_bf16 v[112:115], v[164:167], v[190:193], v[112:115]
	v_mfma_f32_16x16x32_bf16 v[104:107], v[156:159], v[198:201], v[104:107]
	v_mfma_f32_16x16x32_bf16 v[96:99], v[164:167], v[198:201], v[96:99]
	v_mfma_f32_16x16x32_bf16 v[88:91], v[156:159], v[206:209], v[88:91]
	v_mfma_f32_16x16x32_bf16 v[80:83], v[164:167], v[206:209], v[80:83]
	v_mfma_f32_16x16x32_bf16 v[72:75], v[156:159], v[214:217], v[72:75]
	v_mfma_f32_16x16x32_bf16 v[68:71], v[164:167], v[214:217], v[68:71]
	s_setprio 0
	s_setprio 1
	v_mfma_f32_16x16x32_bf16 v[124:127], v[168:171], v[184:187], v[124:127]
	v_mfma_f32_16x16x32_bf16 v[120:123], v[176:179], v[184:187], v[120:123]
	v_mfma_f32_16x16x32_bf16 v[108:111], v[168:171], v[194:197], v[108:111]
	v_mfma_f32_16x16x32_bf16 v[100:103], v[176:179], v[194:197], v[100:103]
	v_mfma_f32_16x16x32_bf16 v[92:95], v[168:171], v[202:205], v[92:95]
	v_mfma_f32_16x16x32_bf16 v[84:87], v[176:179], v[202:205], v[84:87]
	v_mfma_f32_16x16x32_bf16 v[76:79], v[168:171], v[210:213], v[76:79]
	v_mfma_f32_16x16x32_bf16 v[64:67], v[176:179], v[210:213], v[64:67]
	v_mfma_f32_16x16x32_bf16 v[124:127], v[172:175], v[190:193], v[124:127]
	v_mfma_f32_16x16x32_bf16 v[120:123], v[180:183], v[190:193], v[120:123]
	v_mfma_f32_16x16x32_bf16 v[108:111], v[172:175], v[198:201], v[108:111]
	v_mfma_f32_16x16x32_bf16 v[100:103], v[180:183], v[198:201], v[100:103]
	v_mfma_f32_16x16x32_bf16 v[92:95], v[172:175], v[206:209], v[92:95]
	v_mfma_f32_16x16x32_bf16 v[84:87], v[180:183], v[206:209], v[84:87]
	v_mfma_f32_16x16x32_bf16 v[76:79], v[172:175], v[214:217], v[76:79]
	v_mfma_f32_16x16x32_bf16 v[64:67], v[180:183], v[214:217], v[64:67]
	s_setprio 0
	s_barrier
	s_add_i32 s36, s56, s38
	v_lshl_add_u64 v[218:219], v[218:219], 0, s[8:9]
	s_mov_b32 m0, s36
	ds_read_b128 v[184:187], v153 offset:49152
	ds_read_b128 v[190:193], v153 offset:50176
	ds_read_b128 v[194:197], v153 offset:51200
	ds_read_b128 v[198:201], v153 offset:52224
	ds_read_b128 v[202:205], v153 offset:53248
	ds_read_b128 v[206:209], v153 offset:54272
	ds_read_b128 v[210:213], v153 offset:55296
	ds_read_b128 v[214:217], v153 offset:56320
	global_load_lds_dwordx4 v[218:219], off
	s_add_i32 m0, s36, 0x2000
	s_add_u32 s34, s34, 0x40080
	v_lshl_add_u64 v[218:219], v[220:221], 0, s[8:9]
	s_addc_u32 s35, s35, 0
	s_add_i32 s36, s57, s38
	global_load_lds_dwordx4 v[218:219], off
	v_lshl_add_u64 v[218:219], s[34:35], 0, v[130:131]
	s_mov_b32 m0, s36
	s_nop 0
	global_load_lds_dwordx4 v[218:219], off
	v_lshl_add_u64 v[218:219], s[34:35], 0, v[134:135]
	s_add_i32 m0, s36, 0x2000
	s_nop 0
	global_load_lds_dwordx4 v[218:219], off
	v_lshl_add_u64 v[218:219], v[222:223], 0, s[8:9]
	s_mov_b32 m0, s43
	s_nop 0
	global_load_lds_dwordx4 v[218:219], off
	v_lshl_add_u64 v[218:219], v[224:225], 0, s[8:9]
	s_mov_b32 m0, s44
	s_nop 0
	global_load_lds_dwordx4 v[218:219], off
	s_waitcnt vmcnt(8)
	s_waitcnt lgkmcnt(0)
	s_barrier
	s_setprio 1
	s_waitcnt lgkmcnt(0)
	v_mfma_f32_16x16x32_bf16 v[56:59], v[144:147], v[184:187], v[56:59]
	v_mfma_f32_16x16x32_bf16 v[48:51], v[160:163], v[184:187], v[48:51]
	v_mfma_f32_16x16x32_bf16 v[40:43], v[144:147], v[194:197], v[40:43]
	v_mfma_f32_16x16x32_bf16 v[32:35], v[160:163], v[194:197], v[32:35]
	v_mfma_f32_16x16x32_bf16 v[24:27], v[144:147], v[202:205], v[24:27]
	v_mfma_f32_16x16x32_bf16 v[16:19], v[160:163], v[202:205], v[16:19]
	v_mfma_f32_16x16x32_bf16 v[8:11], v[144:147], v[210:213], v[8:11]
	v_mfma_f32_16x16x32_bf16 v[0:3], v[160:163], v[210:213], v[0:3]
	v_mfma_f32_16x16x32_bf16 v[56:59], v[156:159], v[190:193], v[56:59]
	v_mfma_f32_16x16x32_bf16 v[48:51], v[164:167], v[190:193], v[48:51]
	v_mfma_f32_16x16x32_bf16 v[40:43], v[156:159], v[198:201], v[40:43]
	v_mfma_f32_16x16x32_bf16 v[32:35], v[164:167], v[198:201], v[32:35]
	v_mfma_f32_16x16x32_bf16 v[24:27], v[156:159], v[206:209], v[24:27]
	v_mfma_f32_16x16x32_bf16 v[16:19], v[164:167], v[206:209], v[16:19]
	v_mfma_f32_16x16x32_bf16 v[8:11], v[156:159], v[214:217], v[8:11]
	v_mfma_f32_16x16x32_bf16 v[0:3], v[164:167], v[214:217], v[0:3]
	s_setprio 0
	s_setprio 1
	v_mfma_f32_16x16x32_bf16 v[60:63], v[168:171], v[184:187], v[60:63]
	v_mfma_f32_16x16x32_bf16 v[52:55], v[176:179], v[184:187], v[52:55]
	v_mfma_f32_16x16x32_bf16 v[44:47], v[168:171], v[194:197], v[44:47]
	v_mfma_f32_16x16x32_bf16 v[36:39], v[176:179], v[194:197], v[36:39]
	v_mfma_f32_16x16x32_bf16 v[28:31], v[168:171], v[202:205], v[28:31]
	v_mfma_f32_16x16x32_bf16 v[20:23], v[176:179], v[202:205], v[20:23]
	v_mfma_f32_16x16x32_bf16 v[12:15], v[168:171], v[210:213], v[12:15]
	v_mfma_f32_16x16x32_bf16 v[4:7], v[176:179], v[210:213], v[4:7]
	v_mfma_f32_16x16x32_bf16 v[60:63], v[172:175], v[190:193], v[60:63]
	v_mfma_f32_16x16x32_bf16 v[52:55], v[180:183], v[190:193], v[52:55]
	v_mfma_f32_16x16x32_bf16 v[44:47], v[172:175], v[198:201], v[44:47]
	v_mfma_f32_16x16x32_bf16 v[36:39], v[180:183], v[198:201], v[36:39]
	v_mfma_f32_16x16x32_bf16 v[28:31], v[172:175], v[206:209], v[28:31]
	v_mfma_f32_16x16x32_bf16 v[20:23], v[180:183], v[206:209], v[20:23]
	v_mfma_f32_16x16x32_bf16 v[12:15], v[172:175], v[214:217], v[12:15]
	v_mfma_f32_16x16x32_bf16 v[4:7], v[180:183], v[214:217], v[4:7]
	s_setprio 0
	s_add_i32 s55, s55, 2
	s_add_u32 s22, s22, 0x100
	s_addc_u32 s23, s23, 0
	s_add_u32 s53, s53, 0x100
	s_addc_u32 s54, s54, 0
	s_cmp_gt_u32 s55, 13
	s_barrier
	s_cbranch_scc0 .LBB0_980
	v_lshl_add_u32 v236, s20, 8, v148
	v_lshlrev_b32_e32 v236, 2, v236
	global_load_dword v228, v236, s[6:7]
	global_load_dword v229, v236, s[6:7] offset:64
	global_load_dword v230, v236, s[6:7] offset:128
	global_load_dword v231, v236, s[6:7] offset:192
	global_load_dword v232, v236, s[6:7] offset:512
	global_load_dword v233, v236, s[6:7] offset:576
	global_load_dword v234, v236, s[6:7] offset:640
	global_load_dword v235, v236, s[6:7] offset:704
	s_and_b64 vcc, exec, s[10:11]
	s_cbranch_vccz .LBB0_983
	s_barrier

.LBB0_1061:
	ds_read_b128 v[144:147], v187
	ds_read_b128 v[148:151], v187 offset:1024
	ds_read_b128 v[152:155], v187 offset:2048
	ds_read_b128 v[156:159], v187 offset:3072
	ds_read_b128 v[160:163], v189
	ds_read_b128 v[164:167], v189 offset:1024
	ds_read_b128 v[168:171], v189 offset:2048
	ds_read_b128 v[172:175], v189 offset:3072
	s_add_u32 s34, s4, 0xfff50080
	s_addc_u32 s35, s5, -1
	s_cmp_eq_u32 s58, 40
	s_cselect_b32 s37, s19, s35
	s_cselect_b32 s36, s18, s34
	s_cselect_b32 s35, s21, s27
	s_cselect_b32 s34, s20, s23
	v_lshl_add_u64 v[176:177], s[4:5], 0, v[136:137]
	s_add_i32 m0, s40, 0xc000
	ds_read_b128 v[192:195], v190
	ds_read_b128 v[196:199], v190 offset:1024
	ds_read_b128 v[200:203], v190 offset:2048
	ds_read_b128 v[204:207], v190 offset:3072
	ds_read_b128 v[208:211], v190 offset:4096
	ds_read_b128 v[212:215], v190 offset:5120
	ds_read_b128 v[216:219], v190 offset:6144
	ds_read_b128 v[220:223], v190 offset:7168
	global_load_lds_dwordx4 v[176:177], off
	v_lshl_add_u64 v[176:177], s[4:5], 0, v[138:139]
	s_add_i32 m0, s40, 0xe000
	s_nop 0
	global_load_lds_dwordx4 v[176:177], off
	s_waitcnt vmcnt(8)
	s_waitcnt lgkmcnt(0)
	s_barrier
	s_setprio 1
	s_waitcnt lgkmcnt(0)
	v_mfma_f32_16x16x32_bf16 v[124:127], v[144:147], v[192:195], v[124:127]
	v_mfma_f32_16x16x32_bf16 v[120:123], v[152:155], v[192:195], v[120:123]
	v_mfma_f32_16x16x32_bf16 v[108:111], v[144:147], v[200:203], v[108:111]
	v_mfma_f32_16x16x32_bf16 v[104:107], v[152:155], v[200:203], v[104:107]
	v_mfma_f32_16x16x32_bf16 v[92:95], v[144:147], v[208:211], v[92:95]
	v_mfma_f32_16x16x32_bf16 v[88:91], v[152:155], v[208:211], v[88:91]
	v_mfma_f32_16x16x32_bf16 v[76:79], v[144:147], v[216:219], v[76:79]
	v_mfma_f32_16x16x32_bf16 v[72:75], v[152:155], v[216:219], v[72:75]
	v_mfma_f32_16x16x32_bf16 v[124:127], v[148:151], v[196:199], v[124:127]
	v_mfma_f32_16x16x32_bf16 v[120:123], v[156:159], v[196:199], v[120:123]
	v_mfma_f32_16x16x32_bf16 v[108:111], v[148:151], v[204:207], v[108:111]
	v_mfma_f32_16x16x32_bf16 v[104:107], v[156:159], v[204:207], v[104:107]
	v_mfma_f32_16x16x32_bf16 v[92:95], v[148:151], v[212:215], v[92:95]
	v_mfma_f32_16x16x32_bf16 v[88:91], v[156:159], v[212:215], v[88:91]
	v_mfma_f32_16x16x32_bf16 v[76:79], v[148:151], v[220:223], v[76:79]
	v_mfma_f32_16x16x32_bf16 v[72:75], v[156:159], v[220:223], v[72:75]
	s_setprio 0
	s_setprio 1
	v_mfma_f32_16x16x32_bf16 v[116:119], v[160:163], v[192:195], v[116:119]
	v_mfma_f32_16x16x32_bf16 v[112:115], v[168:171], v[192:195], v[112:115]
	v_mfma_f32_16x16x32_bf16 v[100:103], v[160:163], v[200:203], v[100:103]
	v_mfma_f32_16x16x32_bf16 v[96:99], v[168:171], v[200:203], v[96:99]
	v_mfma_f32_16x16x32_bf16 v[84:87], v[160:163], v[208:211], v[84:87]
	v_mfma_f32_16x16x32_bf16 v[80:83], v[168:171], v[208:211], v[80:83]
	v_mfma_f32_16x16x32_bf16 v[68:71], v[160:163], v[216:219], v[68:71]
	v_mfma_f32_16x16x32_bf16 v[64:67], v[168:171], v[216:219], v[64:67]
	v_mfma_f32_16x16x32_bf16 v[116:119], v[164:167], v[196:199], v[116:119]
	v_mfma_f32_16x16x32_bf16 v[112:115], v[172:175], v[196:199], v[112:115]
	v_mfma_f32_16x16x32_bf16 v[100:103], v[164:167], v[204:207], v[100:103]
	v_mfma_f32_16x16x32_bf16 v[96:99], v[172:175], v[204:207], v[96:99]
	v_mfma_f32_16x16x32_bf16 v[84:87], v[164:167], v[212:215], v[84:87]
	v_mfma_f32_16x16x32_bf16 v[80:83], v[172:175], v[212:215], v[80:83]
	v_mfma_f32_16x16x32_bf16 v[68:71], v[164:167], v[220:223], v[68:71]
	v_mfma_f32_16x16x32_bf16 v[64:67], v[172:175], v[220:223], v[64:67]
	s_setprio 0
	s_barrier
	s_add_i32 s59, s54, s39
	v_lshl_add_u64 v[176:177], s[34:35], 0, v[130:131]
	s_mov_b32 m0, s59
	ds_read_b128 v[192:195], v190 offset:16384
	ds_read_b128 v[196:199], v190 offset:17408
	ds_read_b128 v[200:203], v190 offset:18432
	ds_read_b128 v[204:207], v190 offset:19456
	ds_read_b128 v[208:211], v190 offset:20480
	ds_read_b128 v[212:215], v190 offset:21504
	ds_read_b128 v[216:219], v190 offset:22528
	ds_read_b128 v[220:223], v190 offset:23552
	global_load_lds_dwordx4 v[176:177], off
	s_add_i32 m0, s59, 0x2000
	s_add_u32 s60, s34, 0xb0000
	v_lshl_add_u64 v[224:225], s[34:35], 0, v[134:135]
	s_addc_u32 s61, s35, 0
	s_add_i32 s59, s55, s39
	global_load_lds_dwordx4 v[224:225], off
	v_lshl_add_u64 v[226:227], s[60:61], 0, v[130:131]
	s_mov_b32 m0, s59
	v_lshl_add_u64 v[228:229], s[36:37], 0, v[132:133]
	global_load_lds_dwordx4 v[226:227], off
	v_lshl_add_u64 v[226:227], s[60:61], 0, v[134:135]
	s_add_i32 m0, s59, 0x2000
	s_nop 0
	global_load_lds_dwordx4 v[226:227], off
	v_lshl_add_u64 v[226:227], s[36:37], 0, v[128:129]
	s_mov_b32 m0, s40
	s_nop 0
	global_load_lds_dwordx4 v[226:227], off
	s_mov_b32 m0, s41
	s_nop 0
	global_load_lds_dwordx4 v[228:229], off
	s_waitcnt vmcnt(8)
	s_waitcnt lgkmcnt(0)
	s_barrier
	s_setprio 1
	s_waitcnt lgkmcnt(0)
	v_mfma_f32_16x16x32_bf16 v[60:63], v[144:147], v[192:195], v[60:63]
	v_mfma_f32_16x16x32_bf16 v[56:59], v[152:155], v[192:195], v[56:59]
	v_mfma_f32_16x16x32_bf16 v[44:47], v[144:147], v[200:203], v[44:47]
	v_mfma_f32_16x16x32_bf16 v[40:43], v[152:155], v[200:203], v[40:43]
	v_mfma_f32_16x16x32_bf16 v[28:31], v[144:147], v[208:211], v[28:31]
	v_mfma_f32_16x16x32_bf16 v[24:27], v[152:155], v[208:211], v[24:27]
	v_mfma_f32_16x16x32_bf16 v[12:15], v[144:147], v[216:219], v[12:15]
	v_mfma_f32_16x16x32_bf16 v[8:11], v[152:155], v[216:219], v[8:11]
	v_mfma_f32_16x16x32_bf16 v[60:63], v[148:151], v[196:199], v[60:63]
	v_mfma_f32_16x16x32_bf16 v[56:59], v[156:159], v[196:199], v[56:59]
	v_mfma_f32_16x16x32_bf16 v[44:47], v[148:151], v[204:207], v[44:47]
	v_mfma_f32_16x16x32_bf16 v[40:43], v[156:159], v[204:207], v[40:43]
	v_mfma_f32_16x16x32_bf16 v[28:31], v[148:151], v[212:215], v[28:31]
	v_mfma_f32_16x16x32_bf16 v[24:27], v[156:159], v[212:215], v[24:27]
	v_mfma_f32_16x16x32_bf16 v[12:15], v[148:151], v[220:223], v[12:15]
	v_mfma_f32_16x16x32_bf16 v[8:11], v[156:159], v[220:223], v[8:11]
	s_setprio 0
	s_setprio 1
	v_mfma_f32_16x16x32_bf16 v[52:55], v[160:163], v[192:195], v[52:55]
	v_mfma_f32_16x16x32_bf16 v[48:51], v[168:171], v[192:195], v[48:51]
	v_mfma_f32_16x16x32_bf16 v[36:39], v[160:163], v[200:203], v[36:39]
	v_mfma_f32_16x16x32_bf16 v[32:35], v[168:171], v[200:203], v[32:35]
	v_mfma_f32_16x16x32_bf16 v[20:23], v[160:163], v[208:211], v[20:23]
	v_mfma_f32_16x16x32_bf16 v[16:19], v[168:171], v[208:211], v[16:19]
	v_mfma_f32_16x16x32_bf16 v[4:7], v[160:163], v[216:219], v[4:7]
	v_mfma_f32_16x16x32_bf16 v[0:3], v[168:171], v[216:219], v[0:3]
	v_mfma_f32_16x16x32_bf16 v[52:55], v[164:167], v[196:199], v[52:55]
	v_mfma_f32_16x16x32_bf16 v[48:51], v[172:175], v[196:199], v[48:51]
	v_mfma_f32_16x16x32_bf16 v[36:39], v[164:167], v[204:207], v[36:39]
	v_mfma_f32_16x16x32_bf16 v[32:35], v[172:175], v[204:207], v[32:35]
	v_mfma_f32_16x16x32_bf16 v[20:23], v[164:167], v[212:215], v[20:23]
	v_mfma_f32_16x16x32_bf16 v[16:19], v[172:175], v[212:215], v[16:19]
	v_mfma_f32_16x16x32_bf16 v[4:7], v[164:167], v[220:223], v[4:7]
	v_mfma_f32_16x16x32_bf16 v[0:3], v[172:175], v[220:223], v[0:3]
	s_setprio 0
	s_barrier
	s_add_i32 s59, 0, 0x18000
	s_add_i32 s60, 0, 0x1c000
	v_add_u32_e32 v156, s59, v183
	v_add_u32_e32 v172, s60, v183
	ds_read_b128 v[144:147], v156
	ds_read_b128 v[148:151], v156 offset:1024
	ds_read_b128 v[152:155], v156 offset:2048
	ds_read_b128 v[156:159], v156 offset:3072
	ds_read_b128 v[160:163], v172
	ds_read_b128 v[164:167], v172 offset:1024
	ds_read_b128 v[168:171], v172 offset:2048
	ds_read_b128 v[172:175], v172 offset:3072
	s_add_u32 s36, s36, 0xb0000
	s_addc_u32 s37, s37, 0
	s_mov_b32 m0, s42
	v_lshl_add_u64 v[230:231], s[36:37], 0, v[128:129]
	ds_read_b128 v[192:195], v190 offset:32768
	ds_read_b128 v[196:199], v190 offset:33792
	ds_read_b128 v[200:203], v190 offset:34816
	ds_read_b128 v[204:207], v190 offset:35840
	ds_read_b128 v[208:211], v190 offset:36864
	ds_read_b128 v[212:215], v190 offset:37888
	ds_read_b128 v[216:219], v190 offset:38912
	ds_read_b128 v[220:223], v190 offset:39936
	global_load_lds_dwordx4 v[230:231], off
	v_lshl_add_u64 v[230:231], s[36:37], 0, v[132:133]
	s_mov_b32 m0, s43
	s_nop 0
	global_load_lds_dwordx4 v[230:231], off
	s_waitcnt vmcnt(8)
	s_waitcnt lgkmcnt(0)
	s_barrier
	s_setprio 1
	s_waitcnt lgkmcnt(0)
	v_mfma_f32_16x16x32_bf16 v[124:127], v[144:147], v[192:195], v[124:127]
	v_mfma_f32_16x16x32_bf16 v[120:123], v[152:155], v[192:195], v[120:123]
	v_mfma_f32_16x16x32_bf16 v[108:111], v[144:147], v[200:203], v[108:111]
	v_mfma_f32_16x16x32_bf16 v[104:107], v[152:155], v[200:203], v[104:107]
	v_mfma_f32_16x16x32_bf16 v[92:95], v[144:147], v[208:211], v[92:95]
	v_mfma_f32_16x16x32_bf16 v[88:91], v[152:155], v[208:211], v[88:91]
	v_mfma_f32_16x16x32_bf16 v[76:79], v[144:147], v[216:219], v[76:79]
	v_mfma_f32_16x16x32_bf16 v[72:75], v[152:155], v[216:219], v[72:75]
	v_mfma_f32_16x16x32_bf16 v[124:127], v[148:151], v[196:199], v[124:127]
	v_mfma_f32_16x16x32_bf16 v[120:123], v[156:159], v[196:199], v[120:123]
	v_mfma_f32_16x16x32_bf16 v[108:111], v[148:151], v[204:207], v[108:111]
	v_mfma_f32_16x16x32_bf16 v[104:107], v[156:159], v[204:207], v[104:107]
	v_mfma_f32_16x16x32_bf16 v[92:95], v[148:151], v[212:215], v[92:95]
	v_mfma_f32_16x16x32_bf16 v[88:91], v[156:159], v[212:215], v[88:91]
	v_mfma_f32_16x16x32_bf16 v[76:79], v[148:151], v[220:223], v[76:79]
	v_mfma_f32_16x16x32_bf16 v[72:75], v[156:159], v[220:223], v[72:75]
	s_setprio 0
	s_setprio 1
	v_mfma_f32_16x16x32_bf16 v[116:119], v[160:163], v[192:195], v[116:119]
	v_mfma_f32_16x16x32_bf16 v[112:115], v[168:171], v[192:195], v[112:115]
	v_mfma_f32_16x16x32_bf16 v[100:103], v[160:163], v[200:203], v[100:103]
	v_mfma_f32_16x16x32_bf16 v[96:99], v[168:171], v[200:203], v[96:99]
	v_mfma_f32_16x16x32_bf16 v[84:87], v[160:163], v[208:211], v[84:87]
	v_mfma_f32_16x16x32_bf16 v[80:83], v[168:171], v[208:211], v[80:83]
	v_mfma_f32_16x16x32_bf16 v[68:71], v[160:163], v[216:219], v[68:71]
	v_mfma_f32_16x16x32_bf16 v[64:67], v[168:171], v[216:219], v[64:67]
	v_mfma_f32_16x16x32_bf16 v[116:119], v[164:167], v[196:199], v[116:119]
	v_mfma_f32_16x16x32_bf16 v[112:115], v[172:175], v[196:199], v[112:115]
	v_mfma_f32_16x16x32_bf16 v[100:103], v[164:167], v[204:207], v[100:103]
	v_mfma_f32_16x16x32_bf16 v[96:99], v[172:175], v[204:207], v[96:99]
	v_mfma_f32_16x16x32_bf16 v[84:87], v[164:167], v[212:215], v[84:87]
	v_mfma_f32_16x16x32_bf16 v[80:83], v[172:175], v[212:215], v[80:83]
	v_mfma_f32_16x16x32_bf16 v[68:71], v[164:167], v[220:223], v[68:71]
	v_mfma_f32_16x16x32_bf16 v[64:67], v[172:175], v[220:223], v[64:67]
	s_setprio 0
	s_barrier
	s_add_i32 s36, s59, s39
	v_lshl_add_u64 v[176:177], v[176:177], 0, s[14:15]
	s_mov_b32 m0, s36
	ds_read_b128 v[192:195], v190 offset:49152
	ds_read_b128 v[196:199], v190 offset:50176
	ds_read_b128 v[200:203], v190 offset:51200
	ds_read_b128 v[204:207], v190 offset:52224
	ds_read_b128 v[208:211], v190 offset:53248
	ds_read_b128 v[212:215], v190 offset:54272
	ds_read_b128 v[216:219], v190 offset:55296
	ds_read_b128 v[220:223], v190 offset:56320
	global_load_lds_dwordx4 v[176:177], off
	s_add_i32 m0, s36, 0x2000
	s_add_u32 s34, s34, 0xb0080
	v_lshl_add_u64 v[176:177], v[224:225], 0, s[14:15]
	s_addc_u32 s35, s35, 0
	s_add_i32 s36, s60, s39
	global_load_lds_dwordx4 v[176:177], off
	v_lshl_add_u64 v[176:177], s[34:35], 0, v[130:131]
	s_mov_b32 m0, s36
	s_nop 0
	global_load_lds_dwordx4 v[176:177], off
	v_lshl_add_u64 v[176:177], s[34:35], 0, v[134:135]
	s_add_i32 m0, s36, 0x2000
	s_nop 0
	global_load_lds_dwordx4 v[176:177], off
	v_lshl_add_u64 v[176:177], v[226:227], 0, s[14:15]
	s_mov_b32 m0, s47
	s_nop 0
	global_load_lds_dwordx4 v[176:177], off
	v_lshl_add_u64 v[176:177], v[228:229], 0, s[14:15]
	s_mov_b32 m0, s48
	s_nop 0
	global_load_lds_dwordx4 v[176:177], off
	s_waitcnt vmcnt(8)
	s_waitcnt lgkmcnt(0)
	s_barrier
	s_setprio 1
	s_waitcnt lgkmcnt(0)
	v_mfma_f32_16x16x32_bf16 v[60:63], v[144:147], v[192:195], v[60:63]
	v_mfma_f32_16x16x32_bf16 v[56:59], v[152:155], v[192:195], v[56:59]
	v_mfma_f32_16x16x32_bf16 v[44:47], v[144:147], v[200:203], v[44:47]
	v_mfma_f32_16x16x32_bf16 v[40:43], v[152:155], v[200:203], v[40:43]
	v_mfma_f32_16x16x32_bf16 v[28:31], v[144:147], v[208:211], v[28:31]
	v_mfma_f32_16x16x32_bf16 v[24:27], v[152:155], v[208:211], v[24:27]
	v_mfma_f32_16x16x32_bf16 v[12:15], v[144:147], v[216:219], v[12:15]
	v_mfma_f32_16x16x32_bf16 v[8:11], v[152:155], v[216:219], v[8:11]
	v_mfma_f32_16x16x32_bf16 v[60:63], v[148:151], v[196:199], v[60:63]
	v_mfma_f32_16x16x32_bf16 v[56:59], v[156:159], v[196:199], v[56:59]
	v_mfma_f32_16x16x32_bf16 v[44:47], v[148:151], v[204:207], v[44:47]
	v_mfma_f32_16x16x32_bf16 v[40:43], v[156:159], v[204:207], v[40:43]
	v_mfma_f32_16x16x32_bf16 v[28:31], v[148:151], v[212:215], v[28:31]
	v_mfma_f32_16x16x32_bf16 v[24:27], v[156:159], v[212:215], v[24:27]
	v_mfma_f32_16x16x32_bf16 v[12:15], v[148:151], v[220:223], v[12:15]
	v_mfma_f32_16x16x32_bf16 v[8:11], v[156:159], v[220:223], v[8:11]
	s_setprio 0
	s_setprio 1
	v_mfma_f32_16x16x32_bf16 v[52:55], v[160:163], v[192:195], v[52:55]
	v_mfma_f32_16x16x32_bf16 v[48:51], v[168:171], v[192:195], v[48:51]
	v_mfma_f32_16x16x32_bf16 v[36:39], v[160:163], v[200:203], v[36:39]
	v_mfma_f32_16x16x32_bf16 v[32:35], v[168:171], v[200:203], v[32:35]
	v_mfma_f32_16x16x32_bf16 v[20:23], v[160:163], v[208:211], v[20:23]
	v_mfma_f32_16x16x32_bf16 v[16:19], v[168:171], v[208:211], v[16:19]
	v_mfma_f32_16x16x32_bf16 v[4:7], v[160:163], v[216:219], v[4:7]
	v_mfma_f32_16x16x32_bf16 v[0:3], v[168:171], v[216:219], v[0:3]
	v_mfma_f32_16x16x32_bf16 v[52:55], v[164:167], v[196:199], v[52:55]
	v_mfma_f32_16x16x32_bf16 v[48:51], v[172:175], v[196:199], v[48:51]
	v_mfma_f32_16x16x32_bf16 v[36:39], v[164:167], v[204:207], v[36:39]
	v_mfma_f32_16x16x32_bf16 v[32:35], v[172:175], v[204:207], v[32:35]
	v_mfma_f32_16x16x32_bf16 v[20:23], v[164:167], v[212:215], v[20:23]
	v_mfma_f32_16x16x32_bf16 v[16:19], v[172:175], v[212:215], v[16:19]
	v_mfma_f32_16x16x32_bf16 v[4:7], v[164:167], v[220:223], v[4:7]
	v_mfma_f32_16x16x32_bf16 v[0:3], v[172:175], v[220:223], v[0:3]
	s_setprio 0
	s_add_i32 s58, s58, 2
	s_add_u32 s4, s4, 0x100
	s_addc_u32 s5, s5, 0
	s_add_u32 s23, s23, 0x100
	s_addc_u32 s27, s27, 0
	s_cmp_gt_u32 s58, 41
	s_barrier
	s_cbranch_scc0 .LBB0_1061
	s_and_b64 vcc, exec, s[16:17]
	s_cbranch_vccz .LBB0_1064
	s_barrier
